# dprep S0 (wave-0 critical path before the first barrier): beta-gate and a_log loads issued together with the first two S0 loads instead of after the softplus chain behind vmcnt(0) each (4 copies); on
# speedup vs baseline: 1.0028x; 1.0028x over previous
;     template <class T> __device__ __forceinline__ T* w(size_t off) const { return (T*)(pp->ws + off); }
; __device__ __forceinline__ void dprep_unit(const Ctx& c, int l, int b, int chunk, int h) {
;     ...
;     float wq[4][2], wk[4][2], wv[4][2];
;     const float* cw = c.f(I_CONVW) + (size_t)l * 4 * 6144 + h * 128 + 2 * lane;
; #pragma unroll
;     for (int j = 0; j < 4; ++j) { wq[j][0] = cw[j * 6144]; wq[j][1] = cw[j * 6144 + 1]; wk[j][0] = cw[j * 6144 + 2048]; wk[j][1] = cw[j * 6144 + 2049]; wv[j][0] = cw[j * 6144 + 4096]; wv[j][1] = cw[j * 6144 + 4097]; }
;     if (wave == 0) {
;         const float* AB = c.w<float>(WS_AB) + (size_t)(row0 + lane) * 32;
;         const float xx = AB[h] + c.f(I_DTB)[l * 16 + h];
;         const float sp = xx > 20.f ? xx : log1pf(expf(xx));
;         float G = -expf(c.f(I_ALOG)[l * 16 + h]) * sp;
.LBB0_1185:
	s_load_dwordx2 s[14:15], s[90:91], 0x88
	s_lshl_b32 s0, s41, 7
	s_lshl_b32 s0, s0, 2
	s_waitcnt lgkmcnt(0)
	s_add_u32 s0, s14, s0
	s_addc_u32 s1, s15, 0
	v_lshl_add_u64 v[6:7], v[4:5], 2, s[0:1]
	s_movk_i32 s0, 0x6000
	v_add_co_u32_e32 v0, vcc, s0, v6
	s_mov_b32 s0, 0xc000
	s_nop 0
	v_addc_co_u32_e32 v1, vcc, 0, v7, vcc
	v_add_co_u32_e32 v2, vcc, s0, v6
	s_movk_i32 s0, 0x2000
	s_nop 0
	v_addc_co_u32_e32 v3, vcc, 0, v7, vcc
	v_add_co_u32_e32 v22, vcc, s59, v6
	s_nop 1
	v_addc_co_u32_e32 v23, vcc, 0, v7, vcc
	global_load_dwordx2 v[34:35], v[6:7], off
	global_load_dwordx2 v[36:37], v[0:1], off
	global_load_dwordx2 v[38:39], v[2:3], off
	global_load_dwordx2 v[40:41], v[22:23], off
	v_add_co_u32_e32 v0, vcc, s0, v6
	s_mov_b32 s0, 0x8000
	s_nop 0
	v_addc_co_u32_e32 v1, vcc, 0, v7, vcc
	v_add_co_u32_e32 v2, vcc, s0, v6
	s_mov_b32 s0, 0xe000
	s_nop 0
	v_addc_co_u32_e32 v3, vcc, 0, v7, vcc
	v_add_co_u32_e32 v22, vcc, s0, v6
	s_mov_b32 s0, 0x14000
	s_nop 0
	v_addc_co_u32_e32 v23, vcc, 0, v7, vcc
	v_add_co_u32_e32 v24, vcc, s0, v6
	s_movk_i32 s0, 0x4000
	s_nop 0
	v_addc_co_u32_e32 v25, vcc, 0, v7, vcc
	v_add_co_u32_e32 v26, vcc, s0, v6
	global_load_dwordx2 v[0:1], v[0:1], off
	s_nop 0
	global_load_dwordx2 v[2:3], v[2:3], off
	s_nop 0
	global_load_dwordx2 v[22:23], v[22:23], off
	s_nop 0
	global_load_dwordx2 v[24:25], v[24:25], off
	v_addc_co_u32_e32 v27, vcc, 0, v7, vcc
	v_add_co_u32_e32 v28, vcc, 0xa000, v6
	s_nop 1
	v_addc_co_u32_e32 v29, vcc, 0, v7, vcc
	v_add_co_u32_e32 v30, vcc, 0x10000, v6
	s_nop 1
	v_addc_co_u32_e32 v31, vcc, 0, v7, vcc
	v_add_co_u32_e32 v6, vcc, 0x16000, v6
	s_nop 1
	v_addc_co_u32_e32 v7, vcc, 0, v7, vcc
	global_load_dwordx2 v[26:27], v[26:27], off
	s_nop 0
	global_load_dwordx2 v[28:29], v[28:29], off
	s_nop 0
	global_load_dwordx2 v[30:31], v[30:31], off
	s_nop 0
	global_load_dwordx2 v[32:33], v[6:7], off
	v_cndmask_b32_e64 v6, 0, 1, s[34:35]
	v_cmp_ne_u32_e64 s[8:9], 1, v6
	s_andn2_b64 vcc, exec, s[34:35]
	s_cbranch_vccnz .LBB0_1189
	s_lshl_b32 s0, s42, 11
	s_or_b32 s0, s43, s0
	v_add_u32_e32 v6, s0, v66
	v_ashrrev_i32_e32 v7, 31, v6
	v_lshlrev_b64 v[6:7], 7, v[6:7]
	v_lshl_add_u64 v[6:7], s[2:3], 0, v[6:7]
	s_lshl_b32 s16, s41, 2
	s_load_dwordx2 s[0:1], s[90:91], 0x98
	v_lshl_add_u64 v[6:7], v[6:7], 0, s[16:17]
	v_add_co_u32_e32 v60, vcc, 0x32b00000, v6
	s_nop 1
	v_addc_co_u32_e32 v61, vcc, 0, v7, vcc
	global_load_dword v59, v[60:61], off
	global_load_dword v84, v[60:61], off offset:64
	v_mov_b32_e32 v60, s16
	s_waitcnt lgkmcnt(0)
	global_load_dword v60, v60, s[0:1]
	s_load_dwordx2 s[70:71], s[90:91], 0x90
	v_mov_b32_e32 v86, s16
	s_waitcnt lgkmcnt(0)
	global_load_dword v85, v86, s[70:71]
	s_waitcnt vmcnt(0)
	v_add_f32_e32 v59, v59, v60
	v_cmp_nlt_f32_e32 vcc, s6, v59
	s_and_saveexec_b64 s[0:1], vcc
	s_cbranch_execz .LBB0_1188
	v_mul_f32_e32 v60, 0x3fb8aa3b, v59
	v_rndne_f32_e32 v61, v60
	v_sub_f32_e32 v63, v60, v61
	v_fma_f32 v60, v59, s37, -v60
	v_fmac_f32_e32 v60, 0x32a5705f, v59
	v_add_f32_e32 v60, v63, v60
	v_cvt_i32_f32_e32 v61, v61
	v_exp_f32_e32 v60, v60
	v_cmp_ngt_f32_e32 vcc, s39, v59
	s_mov_b32 s6, 0x3f2aaaab
	v_ldexp_f32 v60, v60, v61
	v_cndmask_b32_e32 v60, 0, v60, vcc
	v_cmp_nlt_f32_e32 vcc, s40, v59
	s_nop 1
	v_cndmask_b32_e32 v59, v138, v60, vcc
	v_add_f32_e32 v63, 1.0, v59
	v_add_f32_e32 v60, -1.0, v63
	v_sub_f32_e32 v61, v60, v63
	v_add_f32_e32 v61, 1.0, v61
	v_sub_f32_e32 v60, v59, v60
	v_add_f32_e32 v67, v60, v61
	v_frexp_mant_f32_e32 v68, v63
	v_cvt_f64_f32_e32 v[60:61], v63
	v_frexp_exp_i32_f64_e32 v60, v[60:61]
	v_cmp_gt_f32_e32 vcc, s6, v68
	s_mov_b32 s6, 0x3f317218
	s_nop 0
	v_subbrev_co_u32_e32 v76, vcc, 0, v60, vcc
	v_sub_u32_e32 v60, 0, v76
	v_ldexp_f32 v61, v63, v60
	v_add_f32_e32 v63, -1.0, v61
	v_add_f32_e32 v68, 1.0, v61
	v_ldexp_f32 v60, v67, v60
	v_add_f32_e32 v67, 1.0, v63
	v_add_f32_e32 v69, -1.0, v68
	v_sub_f32_e32 v67, v61, v67
	v_sub_f32_e32 v61, v61, v69
	v_add_f32_e32 v67, v60, v67
	v_add_f32_e32 v60, v60, v61
	v_add_f32_e32 v78, v68, v60
	v_rcp_f32_e32 v80, v78
	v_sub_f32_e32 v61, v68, v78
	v_add_f32_e32 v79, v60, v61
	v_add_f32_e32 v61, v63, v67
	v_sub_f32_e32 v60, v63, v61
	v_add_f32_e32 v63, v67, v60
	v_mul_f32_e32 v67, v61, v80
	v_mul_f32_e32 v68, v78, v67
	v_fma_f32 v70, v67, v78, -v68
	v_fmac_f32_e32 v70, v67, v79
	v_add_f32_e32 v60, v68, v70
	v_sub_f32_e32 v69, v61, v60
	v_pk_add_f32 v[72:73], v[60:61], v[68:69] neg_lo:[0,1] neg_hi:[0,1]
	v_mov_b32_e32 v71, v60
	v_pk_add_f32 v[60:61], v[72:73], v[70:71] neg_lo:[0,1] neg_hi:[0,1]
	s_nop 0
	v_add_f32_e32 v61, v63, v61
	v_add_f32_e32 v60, v60, v61
	v_add_f32_e32 v61, v69, v60
	v_mul_f32_e32 v63, v80, v61
	v_mul_f32_e32 v68, v78, v63
	v_fma_f32 v70, v63, v78, -v68
	v_fmac_f32_e32 v70, v63, v79
	v_sub_f32_e32 v69, v69, v61
	v_add_f32_e32 v78, v60, v69
	v_add_f32_e32 v60, v68, v70
	v_sub_f32_e32 v69, v61, v60
	v_pk_add_f32 v[72:73], v[60:61], v[68:69] neg_lo:[0,1] neg_hi:[0,1]
	v_mov_b32_e32 v71, v60
	v_pk_add_f32 v[60:61], v[72:73], v[70:71] neg_lo:[0,1] neg_hi:[0,1]
	s_nop 0
	v_add_f32_e32 v61, v78, v61
; __device__ __forceinline__ float lane_get(float v, int src_lane) { return __builtin_bit_cast(float, __builtin_amdgcn_ds_bpermute(src_lane << 2, __builtin_bit_cast(int, v))); }
; __device__ __forceinline__ void dprep_unit(const Ctx& c, int l, int b, int chunk, int h) {
;     ...
;         const float sp = xx > 20.f ? xx : log1pf(expf(xx));
;         float G = -expf(c.f(I_ALOG)[l * 16 + h]) * sp;
; #pragma unroll
;         for (int o = 1; o < 64; o <<= 1) { const float t = lane_get(G, lane - o); if (lane >= o) G += t; }
;         Gs[lane] = G; betas[lane] = 1.0f / (1.0f + expf(-AB[16 + h]));
	v_add_f32_e32 v60, v60, v61
	v_add_f32_e32 v61, v67, v63
	v_add_f32_e32 v60, v69, v60
	v_sub_f32_e32 v67, v61, v67
	v_mul_f32_e32 v60, v80, v60
	v_sub_f32_e32 v63, v63, v67
	v_add_f32_e32 v67, v63, v60
	v_add_f32_e32 v68, v61, v67
	v_mul_f32_e32 v70, v68, v68
	v_fmamk_f32 v60, v70, 0x3e9b6dac, v223
	v_fmaak_f32 v229, v70, v60, 0x3f2aaada
	v_cvt_f32_i32_e32 v60, v76
	v_sub_f32_e32 v61, v68, v61
	v_sub_f32_e32 v61, v67, v61
	v_ldexp_f32 v67, v61, 1
	v_mul_f32_e32 v61, v68, v70
	v_pk_mul_f32 v[70:71], v[60:61], v[228:229]
	v_ldexp_f32 v69, v68, 1
	v_fma_f32 v68, v60, s6, -v70
	v_fmac_f32_e32 v68, 0xb102e308, v60
	v_pk_add_f32 v[60:61], v[70:71], v[68:69]
	v_mov_b32_e32 v72, v70
	v_sub_f32_e32 v63, v61, v69
	v_sub_f32_e32 v63, v71, v63
	v_add_f32_e32 v73, v67, v63
	v_pk_add_f32 v[70:71], v[60:61], v[70:71] neg_lo:[0,1] neg_hi:[0,1]
	v_pk_add_f32 v[78:79], v[60:61], v[72:73]
	v_mov_b32_e32 v69, v60
	v_mov_b32_e32 v71, v79
	v_pk_add_f32 v[80:81], v[68:69], v[70:71] neg_lo:[0,1] neg_hi:[0,1]
	v_pk_add_f32 v[68:69], v[68:69], v[70:71]
	v_mov_b32_e32 v72, v73
	v_pk_add_f32 v[70:71], v[68:69], v[60:61] op_sel:[1,0] op_sel_hi:[0,1] neg_lo:[0,1] neg_hi:[0,1]
	v_pk_add_f32 v[82:83], v[78:79], v[70:71] op_sel_hi:[1,0] neg_lo:[0,1] neg_hi:[0,1]
	v_mov_b32_e32 v78, v79
	v_mov_b32_e32 v79, v69
	v_pk_mov_b32 v[70:71], v[60:61], v[70:71] op_sel:[1,0]
	v_mov_b32_e32 v73, v60
	v_pk_add_f32 v[70:71], v[78:79], v[70:71] neg_lo:[0,1] neg_hi:[0,1]
	v_mov_b32_e32 v82, v80
	v_pk_add_f32 v[60:61], v[72:73], v[70:71] neg_lo:[0,1] neg_hi:[0,1]
	v_mov_b32_e32 v81, v69
	v_pk_add_f32 v[70:71], v[82:83], v[60:61]
	s_mov_b32 s6, 0x7f800000
	v_pk_add_f32 v[72:73], v[70:71], v[70:71] op_sel:[0,1] op_sel_hi:[1,0]
	v_cmp_neq_f32_e32 vcc, s6, v59
	v_pk_add_f32 v[68:69], v[68:69], v[72:73] op_sel:[1,0] op_sel_hi:[0,1]
	v_mov_b32_e32 v71, v68
	v_pk_add_f32 v[78:79], v[70:71], v[80:81] neg_lo:[0,1] neg_hi:[0,1]
	v_mov_b32_e32 v61, v72
	v_sub_f32_e32 v63, v70, v78
	v_pk_add_f32 v[60:61], v[60:61], v[78:79] neg_lo:[0,1] neg_hi:[0,1]
	v_sub_f32_e32 v63, v80, v63
	v_add_f32_e32 v60, v60, v63
	v_add_f32_e32 v60, v60, v61
	v_add_f32_e32 v60, v68, v60
	s_mov_b32 s6, 0x33800000
	v_cndmask_b32_e32 v60, v138, v60, vcc
	v_cmp_lt_f32_e64 vcc, |v59|, s6
	s_nop 1
	v_cndmask_b32_e32 v59, v60, v59, vcc
.LBB0_1188:
	s_or_b64 exec, exec, s[0:1]
	s_mov_b64 s[0:1], 0x32b00000
	v_lshl_add_u64 v[6:7], v[6:7], 0, s[0:1]
	s_load_dwordx2 s[0:1], s[90:91], 0x90
	v_mov_b32_e32 v60, s16
	v_mov_b32_e32 v6, v84
	s_waitcnt vmcnt(0)
	v_mul_f32_e32 v7, 0xbfb8aa3b, v6
	s_waitcnt lgkmcnt(0)
	v_mov_b32_e32 v60, v85
	s_waitcnt vmcnt(0)
	v_mul_f32_e32 v61, 0x3fb8aa3b, v60
	v_fma_f32 v63, v60, s37, -v61
	v_rndne_f32_e32 v67, v61
	v_fmac_f32_e32 v63, 0x32a5705f, v60
	v_sub_f32_e32 v61, v61, v67
	v_add_f32_e32 v61, v61, v63
	v_exp_f32_e32 v61, v61
	v_cvt_i32_f32_e32 v63, v67
	v_cmp_ngt_f32_e32 vcc, s39, v60
	v_ldexp_f32 v61, v61, v63
	s_nop 0
	v_cndmask_b32_e32 v61, 0, v61, vcc
	v_cmp_nlt_f32_e32 vcc, s40, v60
	v_lshlrev_b32_e32 v63, 2, v66
	v_add_u32_e32 v67, -4, v63
	v_cndmask_b32_e32 v60, v138, v61, vcc
	v_mul_f32_e64 v61, v59, -v60
	ds_bpermute_b32 v67, v67, v61
	v_cmp_gt_i32_e32 vcc, 1, v66
	s_waitcnt lgkmcnt(0)
	v_fma_f32 v59, v59, -v60, v67
	v_cndmask_b32_e32 v59, v59, v61, vcc
	v_add_u32_e32 v60, -8, v63
	ds_bpermute_b32 v60, v60, v59
	v_cmp_gt_i32_e32 vcc, 2, v66
	v_rndne_f32_e32 v61, v7
	s_waitcnt lgkmcnt(0)
	v_add_f32_e32 v60, v59, v60
	v_cndmask_b32_e32 v59, v60, v59, vcc
	v_add_u32_e32 v60, -16, v63
	ds_bpermute_b32 v60, v60, v59
	v_cmp_gt_i32_e32 vcc, 4, v66
	s_waitcnt lgkmcnt(0)
	v_add_f32_e32 v60, v59, v60
	v_cndmask_b32_e32 v59, v60, v59, vcc
	v_subrev_u32_e32 v60, 32, v63
	ds_bpermute_b32 v60, v60, v59
	v_cmp_gt_i32_e32 vcc, 8, v66
	s_waitcnt lgkmcnt(0)
	v_add_f32_e32 v60, v59, v60
	v_cndmask_b32_e32 v59, v60, v59, vcc
	v_subrev_u32_e32 v60, 64, v63
	ds_bpermute_b32 v60, v60, v59
	v_cmp_gt_i32_e32 vcc, 16, v66
	s_waitcnt lgkmcnt(0)
	v_add_f32_e32 v60, v59, v60
	v_cndmask_b32_e32 v59, v60, v59, vcc
	v_add_u32_e32 v60, 0xffffff80, v63
	ds_bpermute_b32 v60, v60, v59
	v_cmp_gt_i32_e32 vcc, 32, v66
	s_waitcnt lgkmcnt(0)
	v_add_f32_e32 v60, v59, v60
	v_cndmask_b32_e32 v59, v60, v59, vcc
	v_add_u32_e32 v60, v156, v63
	v_sub_f32_e32 v63, v7, v61
	v_fma_f32 v7, v6, s63, -v7
	v_fmac_f32_e32 v7, 0xb2a5705f, v6
	v_add_f32_e32 v7, v63, v7
	v_exp_f32_e32 v7, v7
	v_cvt_i32_f32_e32 v61, v61
	v_cmp_nlt_f32_e32 vcc, s64, v6
	v_ldexp_f32 v7, v7, v61
	s_nop 0
	v_cndmask_b32_e32 v7, 0, v7, vcc
	v_cmp_ngt_f32_e32 vcc, s65, v6
	s_nop 1
	v_cndmask_b32_e32 v6, v138, v7, vcc
	v_add_f32_e32 v6, 1.0, v6
	v_div_scale_f32 v7, s[0:1], v6, v6, 1.0
	v_rcp_f32_e32 v61, v7
	s_nop 0
	v_fma_f32 v63, -v7, v61, 1.0
	v_fmac_f32_e32 v61, v63, v61
	v_div_scale_f32 v63, vcc, 1.0, v6, 1.0
	v_mul_f32_e32 v67, v63, v61
	v_fma_f32 v68, -v7, v67, v63
	v_fmac_f32_e32 v67, v68, v61
	v_fma_f32 v7, -v7, v67, v63
	v_div_fmas_f32 v7, v7, v61, v67
	v_div_fixup_f32 v6, v7, v6, 1.0
	ds_write2st64_b32 v60, v59, v6 offset1:1

;     template <class T> __device__ __forceinline__ T* w(size_t off) const { return (T*)(pp->ws + off); }
; __device__ __forceinline__ void dprep_unit(const Ctx& c, int l, int b, int chunk, int h) {
;     ...
;     float wq[4][2], wk[4][2], wv[4][2];
;     const float* cw = c.f(I_CONVW) + (size_t)l * 4 * 6144 + h * 128 + 2 * lane;
; #pragma unroll
;     for (int j = 0; j < 4; ++j) { wq[j][0] = cw[j * 6144]; wq[j][1] = cw[j * 6144 + 1]; wk[j][0] = cw[j * 6144 + 2048]; wk[j][1] = cw[j * 6144 + 2049]; wv[j][0] = cw[j * 6144 + 4096]; wv[j][1] = cw[j * 6144 + 4097]; }
;     if (wave == 0) {
;         const float* AB = c.w<float>(WS_AB) + (size_t)(row0 + lane) * 32;
;         const float xx = AB[h] + c.f(I_DTB)[l * 16 + h];
;         const float sp = xx > 20.f ? xx : log1pf(expf(xx));
;         float G = -expf(c.f(I_ALOG)[l * 16 + h]) * sp;
.LBB0_1246:
	s_lshl_b32 s0, s34, 7
	s_lshl_b32 s0, s0, 2
	s_add_u32 s0, s14, s0
	s_addc_u32 s1, s15, 0
	v_lshl_add_u64 v[38:39], v[4:5], 2, s[0:1]
	s_movk_i32 s0, 0x6000
	v_add_co_u32_e32 v0, vcc, s0, v38
	s_mov_b32 s0, 0xc000
	s_nop 0
	v_addc_co_u32_e32 v1, vcc, 0, v39, vcc
	v_add_co_u32_e32 v2, vcc, s0, v38
	s_movk_i32 s0, 0x2000
	s_nop 0
	v_addc_co_u32_e32 v3, vcc, 0, v39, vcc
	v_add_co_u32_e32 v4, vcc, s27, v38
	s_mov_b32 s30, 0x3fb8aa3b
	s_nop 0
	v_addc_co_u32_e32 v5, vcc, 0, v39, vcc
	global_load_dwordx2 v[46:47], v[38:39], off
	global_load_dwordx2 v[48:49], v[0:1], off
	global_load_dwordx2 v[50:51], v[2:3], off
	global_load_dwordx2 v[52:53], v[4:5], off
	v_add_co_u32_e32 v0, vcc, s0, v38
	s_mov_b32 s0, 0x8000
	s_nop 0
	v_addc_co_u32_e32 v1, vcc, 0, v39, vcc
	v_add_co_u32_e32 v2, vcc, s0, v38
	s_mov_b32 s0, 0xe000
	s_nop 0
	v_addc_co_u32_e32 v3, vcc, 0, v39, vcc
	v_add_co_u32_e32 v4, vcc, s0, v38
	s_mov_b32 s0, 0x14000
	s_nop 0
	v_addc_co_u32_e32 v5, vcc, 0, v39, vcc
	v_add_co_u32_e32 v36, vcc, s0, v38
	s_movk_i32 s0, 0x4000
	s_nop 0
	v_addc_co_u32_e32 v37, vcc, 0, v39, vcc
	v_add_co_u32_e32 v40, vcc, s0, v38
	global_load_dwordx2 v[0:1], v[0:1], off
	s_nop 0
	global_load_dwordx2 v[2:3], v[2:3], off
	s_nop 0
	global_load_dwordx2 v[4:5], v[4:5], off
	s_nop 0
	global_load_dwordx2 v[36:37], v[36:37], off
	v_addc_co_u32_e32 v41, vcc, 0, v39, vcc
	v_add_co_u32_e32 v42, vcc, 0xa000, v38
	s_mov_b32 s31, 0xc2ce8ed0
	s_nop 0
	v_addc_co_u32_e32 v43, vcc, 0, v39, vcc
	v_add_co_u32_e32 v44, vcc, 0x10000, v38
	s_nop 1
	v_addc_co_u32_e32 v45, vcc, 0, v39, vcc
	v_add_co_u32_e32 v54, vcc, 0x16000, v38
	s_nop 1
	v_addc_co_u32_e32 v55, vcc, 0, v39, vcc
	global_load_dwordx2 v[38:39], v[40:41], off
	s_nop 0
	global_load_dwordx2 v[40:41], v[42:43], off
	s_nop 0
	global_load_dwordx2 v[42:43], v[44:45], off
	s_nop 0
	global_load_dwordx2 v[44:45], v[54:55], off
	s_and_b64 vcc, exec, s[8:9]
	s_cbranch_vccnz .LBB0_1250
	s_lshl_b32 s0, s42, 11
	s_or_b32 s0, s43, s0
	v_add_u32_e32 v54, s0, v66
	v_ashrrev_i32_e32 v55, 31, v54
	s_load_dwordx2 s[0:1], s[90:91], 0x98
	v_lshlrev_b64 v[54:55], 7, v[54:55]
	v_lshl_add_u64 v[54:55], s[2:3], 0, v[54:55]
	s_lshl_b32 s16, s41, 2
	v_lshl_add_u64 v[54:55], v[54:55], 0, s[16:17]
	s_mov_b64 s[4:5], 0x32b00000
	v_lshl_add_u64 v[54:55], v[54:55], 0, s[4:5]
	v_mov_b32_e32 v63, s16
	global_load_dword v61, v[54:55], off offset:32
	global_load_dword v112, v[54:55], off offset:96
	s_waitcnt lgkmcnt(0)
	global_load_dword v63, v63, s[0:1] offset:32
	s_load_dwordx2 s[70:71], s[90:91], 0x90
	v_mov_b32_e32 v114, s16
	s_waitcnt lgkmcnt(0)
	global_load_dword v113, v114, s[70:71] offset:32
	s_waitcnt vmcnt(0)
	v_add_f32_e32 v61, v61, v63
	v_cmp_nlt_f32_e32 vcc, s29, v61
	s_and_saveexec_b64 s[0:1], vcc
	s_cbranch_execz .LBB0_1249
	v_mul_f32_e32 v63, 0x3fb8aa3b, v61
	v_rndne_f32_e32 v94, v63
	v_sub_f32_e32 v95, v63, v94
	v_fma_f32 v63, v61, s30, -v63
	v_fmac_f32_e32 v63, 0x32a5705f, v61
	v_add_f32_e32 v63, v95, v63
	v_cvt_i32_f32_e32 v94, v94
	v_exp_f32_e32 v63, v63
	v_cmp_ngt_f32_e32 vcc, s31, v61
	s_mov_b32 s4, 0x3f2aaaab
	v_ldexp_f32 v63, v63, v94
	v_cndmask_b32_e32 v63, 0, v63, vcc
	v_cmp_nlt_f32_e32 vcc, s62, v61
	s_nop 1
	v_cndmask_b32_e32 v61, v138, v63, vcc
	v_add_f32_e32 v63, 1.0, v61
	v_add_f32_e32 v94, -1.0, v63
	v_sub_f32_e32 v95, v94, v63
	v_add_f32_e32 v95, 1.0, v95
	v_sub_f32_e32 v94, v61, v94
	v_add_f32_e32 v98, v94, v95
	v_frexp_mant_f32_e32 v99, v63
	v_cvt_f64_f32_e32 v[94:95], v63
	v_frexp_exp_i32_f64_e32 v94, v[94:95]
	v_cmp_gt_f32_e32 vcc, s4, v99
	s_mov_b32 s4, 0x3f317218
	s_nop 0
	v_subbrev_co_u32_e32 v103, vcc, 0, v94, vcc
	v_sub_u32_e32 v94, 0, v103
	v_ldexp_f32 v63, v63, v94
	v_ldexp_f32 v94, v98, v94
	v_add_f32_e32 v98, -1.0, v63
	v_add_f32_e32 v95, 1.0, v98
	v_sub_f32_e32 v95, v63, v95
	v_add_f32_e32 v99, v94, v95
	v_add_f32_e32 v95, 1.0, v63
	v_add_f32_e32 v100, -1.0, v95
	v_sub_f32_e32 v63, v63, v100
	v_add_f32_e32 v63, v94, v63
	v_add_f32_e32 v106, v95, v63
	v_rcp_f32_e32 v107, v106
	v_sub_f32_e32 v94, v95, v106
	v_add_f32_e32 v95, v98, v99
	v_add_f32_e32 v63, v63, v94
	v_mul_f32_e32 v109, v95, v107
	v_sub_f32_e32 v94, v98, v95
	v_mul_f32_e32 v98, v106, v109
	v_fma_f32 v100, v109, v106, -v98
	v_fmac_f32_e32 v100, v109, v63
	v_add_f32_e32 v108, v99, v94
	v_add_f32_e32 v94, v98, v100
	v_sub_f32_e32 v99, v95, v94
	v_pk_add_f32 v[104:105], v[94:95], v[98:99] neg_lo:[0,1] neg_hi:[0,1]
	v_mov_b32_e32 v101, v94
	v_pk_add_f32 v[94:95], v[104:105], v[100:101] neg_lo:[0,1] neg_hi:[0,1]
	s_nop 0
	v_add_f32_e32 v95, v108, v95
	v_add_f32_e32 v94, v94, v95
	v_add_f32_e32 v95, v99, v94
	v_mul_f32_e32 v108, v107, v95
	v_mul_f32_e32 v98, v106, v108
	v_fma_f32 v100, v108, v106, -v98
	v_fmac_f32_e32 v100, v108, v63
	v_sub_f32_e32 v63, v99, v95
	v_add_f32_e32 v63, v94, v63
	v_add_f32_e32 v94, v98, v100
	v_sub_f32_e32 v99, v95, v94
	v_pk_add_f32 v[104:105], v[94:95], v[98:99] neg_lo:[0,1] neg_hi:[0,1]
	v_mov_b32_e32 v101, v94
	v_pk_add_f32 v[94:95], v[104:105], v[100:101] neg_lo:[0,1] neg_hi:[0,1]
	s_nop 0
	v_add_f32_e32 v63, v63, v95
; __device__ __forceinline__ float lane_get(float v, int src_lane) { return __builtin_bit_cast(float, __builtin_amdgcn_ds_bpermute(src_lane << 2, __builtin_bit_cast(int, v))); }
; __device__ __forceinline__ void dprep_unit(const Ctx& c, int l, int b, int chunk, int h) {
;     ...
;         const float sp = xx > 20.f ? xx : log1pf(expf(xx));
;         float G = -expf(c.f(I_ALOG)[l * 16 + h]) * sp;
; #pragma unroll
;         for (int o = 1; o < 64; o <<= 1) { const float t = lane_get(G, lane - o); if (lane >= o) G += t; }
;         Gs[lane] = G; betas[lane] = 1.0f / (1.0f + expf(-AB[16 + h]));
	v_add_f32_e32 v63, v94, v63
	v_add_f32_e32 v95, v109, v108
	v_add_f32_e32 v63, v99, v63
	v_sub_f32_e32 v94, v95, v109
	v_mul_f32_e32 v63, v107, v63
	v_sub_f32_e32 v94, v108, v94
	v_add_f32_e32 v98, v94, v63
	v_add_f32_e32 v100, v95, v98
	v_cvt_f32_i32_e32 v94, v103
	v_mul_f32_e32 v101, v100, v100
	v_sub_f32_e32 v95, v100, v95
	v_fmamk_f32 v63, v101, 0x3e9b6dac, v223
	v_sub_f32_e32 v95, v98, v95
	v_fmaak_f32 v229, v101, v63, 0x3f2aaada
	v_ldexp_f32 v103, v95, 1
	v_mul_f32_e32 v95, v100, v101
	v_ldexp_f32 v99, v100, 1
	v_pk_mul_f32 v[100:101], v[94:95], v[228:229]
	s_nop 0
	v_fma_f32 v98, v94, s4, -v100
	v_fmac_f32_e32 v98, 0xb102e308, v94
	v_pk_add_f32 v[94:95], v[100:101], v[98:99]
	v_mov_b32_e32 v104, v100
	v_sub_f32_e32 v63, v95, v99
	v_sub_f32_e32 v63, v101, v63
	v_add_f32_e32 v105, v103, v63
	v_pk_add_f32 v[100:101], v[94:95], v[100:101] neg_lo:[0,1] neg_hi:[0,1]
	v_pk_add_f32 v[106:107], v[94:95], v[104:105]
	v_mov_b32_e32 v99, v94
	v_mov_b32_e32 v101, v107
	v_pk_add_f32 v[108:109], v[98:99], v[100:101] neg_lo:[0,1] neg_hi:[0,1]
	v_pk_add_f32 v[98:99], v[98:99], v[100:101]
	v_mov_b32_e32 v104, v105
	v_pk_add_f32 v[100:101], v[98:99], v[94:95] op_sel:[1,0] op_sel_hi:[0,1] neg_lo:[0,1] neg_hi:[0,1]
	v_pk_add_f32 v[110:111], v[106:107], v[100:101] op_sel_hi:[1,0] neg_lo:[0,1] neg_hi:[0,1]
	v_mov_b32_e32 v106, v107
	v_mov_b32_e32 v107, v99
	v_pk_mov_b32 v[100:101], v[94:95], v[100:101] op_sel:[1,0]
	v_mov_b32_e32 v105, v94
	v_pk_add_f32 v[100:101], v[106:107], v[100:101] neg_lo:[0,1] neg_hi:[0,1]
	v_mov_b32_e32 v110, v108
	v_pk_add_f32 v[94:95], v[104:105], v[100:101] neg_lo:[0,1] neg_hi:[0,1]
	v_mov_b32_e32 v109, v99
	v_pk_add_f32 v[100:101], v[110:111], v[94:95]
	s_mov_b32 s4, 0x7f800000
	v_pk_add_f32 v[104:105], v[100:101], v[100:101] op_sel:[0,1] op_sel_hi:[1,0]
	v_cmp_neq_f32_e32 vcc, s4, v61
	v_pk_add_f32 v[98:99], v[98:99], v[104:105] op_sel:[1,0] op_sel_hi:[0,1]
	v_mov_b32_e32 v101, v98
	v_pk_add_f32 v[106:107], v[100:101], v[108:109] neg_lo:[0,1] neg_hi:[0,1]
	v_mov_b32_e32 v95, v104
	v_sub_f32_e32 v63, v100, v106
	v_pk_add_f32 v[94:95], v[94:95], v[106:107] neg_lo:[0,1] neg_hi:[0,1]
	v_sub_f32_e32 v63, v108, v63
	v_add_f32_e32 v63, v94, v63
	v_add_f32_e32 v63, v63, v95
	v_add_f32_e32 v63, v98, v63
	s_mov_b32 s4, 0x33800000
	v_cndmask_b32_e32 v63, v138, v63, vcc
	v_cmp_lt_f32_e64 vcc, |v61|, s4
	s_nop 1
	v_cndmask_b32_e32 v61, v63, v61, vcc
.LBB0_1249:
	s_or_b64 exec, exec, s[0:1]
	s_load_dwordx2 s[0:1], s[90:91], 0x90
	v_mov_b32_e32 v63, s16
	v_mov_b32_e32 v54, v112
	s_waitcnt vmcnt(0)
	v_mul_f32_e32 v55, 0xbfb8aa3b, v54
	s_waitcnt lgkmcnt(0)
	v_mov_b32_e32 v63, v113
	s_waitcnt vmcnt(0)
	v_mul_f32_e32 v94, 0x3fb8aa3b, v63
	v_fma_f32 v95, v63, s30, -v94
	v_rndne_f32_e32 v98, v94
	v_fmac_f32_e32 v95, 0x32a5705f, v63
	v_sub_f32_e32 v94, v94, v98
	v_add_f32_e32 v94, v94, v95
	v_exp_f32_e32 v94, v94
	v_cvt_i32_f32_e32 v95, v98
	v_cmp_ngt_f32_e32 vcc, s31, v63
	v_ldexp_f32 v94, v94, v95
	s_nop 0
	v_cndmask_b32_e32 v94, 0, v94, vcc
	v_cmp_nlt_f32_e32 vcc, s62, v63
	v_add_u32_e32 v95, -4, v60
	s_nop 0
	v_cndmask_b32_e32 v63, v138, v94, vcc
	v_mul_f32_e64 v94, v61, -v63
	ds_bpermute_b32 v95, v95, v94
	v_cmp_gt_i32_e32 vcc, 1, v66
	s_waitcnt lgkmcnt(0)
	v_fma_f32 v61, v61, -v63, v95
	v_cndmask_b32_e32 v61, v61, v94, vcc
	v_add_u32_e32 v63, -8, v60
	ds_bpermute_b32 v63, v63, v61
	v_cmp_gt_i32_e32 vcc, 2, v66
	s_waitcnt lgkmcnt(0)
	v_add_f32_e32 v63, v61, v63
	v_cndmask_b32_e32 v61, v63, v61, vcc
	v_add_u32_e32 v63, -16, v60
	ds_bpermute_b32 v63, v63, v61
	v_cmp_gt_i32_e32 vcc, 4, v66
	s_waitcnt lgkmcnt(0)
	v_add_f32_e32 v63, v61, v63
	v_cndmask_b32_e32 v61, v63, v61, vcc
	v_subrev_u32_e32 v63, 32, v60
	ds_bpermute_b32 v63, v63, v61
	v_cmp_gt_i32_e32 vcc, 8, v66
	s_waitcnt lgkmcnt(0)
	v_add_f32_e32 v63, v61, v63
	v_cndmask_b32_e32 v61, v63, v61, vcc
	v_subrev_u32_e32 v63, 64, v60
	ds_bpermute_b32 v63, v63, v61
	v_cmp_gt_i32_e32 vcc, 16, v66
	v_add_u32_e32 v60, 0xffffff80, v60
	s_waitcnt lgkmcnt(0)
	v_add_f32_e32 v63, v61, v63
	v_cndmask_b32_e32 v61, v63, v61, vcc
	v_rndne_f32_e32 v63, v55
	v_sub_f32_e32 v94, v55, v63
	v_fma_f32 v55, v54, s63, -v55
	ds_bpermute_b32 v60, v60, v61
	v_fmac_f32_e32 v55, 0xb2a5705f, v54
	v_add_f32_e32 v55, v94, v55
	v_exp_f32_e32 v55, v55
	v_cvt_i32_f32_e32 v63, v63
	v_cmp_gt_i32_e32 vcc, 32, v66
	s_waitcnt lgkmcnt(0)
	v_add_f32_e32 v60, v61, v60
	v_ldexp_f32 v55, v55, v63
	v_cndmask_b32_e32 v60, v60, v61, vcc
	v_cmp_nlt_f32_e32 vcc, s64, v54
	v_lshl_add_u32 v61, v66, 2, v169
	s_nop 0
	v_cndmask_b32_e32 v55, 0, v55, vcc
	v_cmp_ngt_f32_e32 vcc, s65, v54
	s_nop 1
	v_cndmask_b32_e32 v54, v138, v55, vcc
	v_add_f32_e32 v54, 1.0, v54
	v_div_scale_f32 v55, s[0:1], v54, v54, 1.0
	v_rcp_f32_e32 v63, v55
	s_nop 0
	v_fma_f32 v94, -v55, v63, 1.0
	v_fmac_f32_e32 v63, v94, v63
	v_div_scale_f32 v94, vcc, 1.0, v54, 1.0
	v_mul_f32_e32 v95, v94, v63
	v_fma_f32 v98, -v55, v95, v94
	v_fmac_f32_e32 v95, v98, v63
	v_fma_f32 v55, -v55, v95, v94
	v_div_fmas_f32 v55, v55, v63, v95
	v_div_fixup_f32 v54, v55, v54, 1.0
	ds_write2st64_b32 v61, v60, v54 offset1:1

;     template <class T> __device__ __forceinline__ T* w(size_t off) const { return (T*)(pp->ws + off); }
; __device__ __forceinline__ void dprep_unit(const Ctx& c, int l, int b, int chunk, int h) {
;     ...
;     float wq[4][2], wk[4][2], wv[4][2];
;     const float* cw = c.f(I_CONVW) + (size_t)l * 4 * 6144 + h * 128 + 2 * lane;
; #pragma unroll
;     for (int j = 0; j < 4; ++j) { wq[j][0] = cw[j * 6144]; wq[j][1] = cw[j * 6144 + 1]; wk[j][0] = cw[j * 6144 + 2048]; wk[j][1] = cw[j * 6144 + 2049]; wv[j][0] = cw[j * 6144 + 4096]; wv[j][1] = cw[j * 6144 + 4097]; }
;     if (wave == 0) {
;         const float* AB = c.w<float>(WS_AB) + (size_t)(row0 + lane) * 32;
;         const float xx = AB[h] + c.f(I_DTB)[l * 16 + h];
;         const float sp = xx > 20.f ? xx : log1pf(expf(xx));
;         float G = -expf(c.f(I_ALOG)[l * 16 + h]) * sp;
.LBB0_2708:
	s_load_dwordx2 s[0:1], s[90:91], 0x88
	s_lshl_b32 s6, s39, 7
	s_waitcnt lgkmcnt(0)
	s_add_u32 s46, s0, 0x18000
	s_addc_u32 s47, s1, 0
	s_lshl_b32 s0, s6, 2
	s_add_u32 s0, s46, s0
	s_addc_u32 s1, s47, 0
	v_lshl_add_u64 v[6:7], v[4:5], 2, s[0:1]
	s_movk_i32 s0, 0x6000
	v_add_co_u32_e32 v0, vcc, s0, v6
	s_mov_b32 s0, 0xc000
	s_nop 0
	v_addc_co_u32_e32 v1, vcc, 0, v7, vcc
	v_add_co_u32_e32 v2, vcc, s0, v6
	s_movk_i32 s0, 0x2000
	s_nop 0
	v_addc_co_u32_e32 v3, vcc, 0, v7, vcc
	v_add_co_u32_e32 v22, vcc, s35, v6
	s_nop 1
	v_addc_co_u32_e32 v23, vcc, 0, v7, vcc
	global_load_dwordx2 v[34:35], v[6:7], off
	global_load_dwordx2 v[36:37], v[0:1], off
	global_load_dwordx2 v[38:39], v[2:3], off
	global_load_dwordx2 v[40:41], v[22:23], off
	v_add_co_u32_e32 v0, vcc, s0, v6
	s_mov_b32 s0, 0x8000
	s_nop 0
	v_addc_co_u32_e32 v1, vcc, 0, v7, vcc
	v_add_co_u32_e32 v2, vcc, s0, v6
	s_mov_b32 s0, 0xe000
	s_nop 0
	v_addc_co_u32_e32 v3, vcc, 0, v7, vcc
	v_add_co_u32_e32 v22, vcc, s0, v6
	s_mov_b32 s0, 0x14000
	s_nop 0
	v_addc_co_u32_e32 v23, vcc, 0, v7, vcc
	v_add_co_u32_e32 v24, vcc, s0, v6
	s_movk_i32 s0, 0x4000
	s_nop 0
	v_addc_co_u32_e32 v25, vcc, 0, v7, vcc
	v_add_co_u32_e32 v26, vcc, s0, v6
	global_load_dwordx2 v[0:1], v[0:1], off
	s_nop 0
	global_load_dwordx2 v[2:3], v[2:3], off
	s_nop 0
	global_load_dwordx2 v[22:23], v[22:23], off
	s_nop 0
	global_load_dwordx2 v[24:25], v[24:25], off
	v_addc_co_u32_e32 v27, vcc, 0, v7, vcc
	v_add_co_u32_e32 v28, vcc, 0xa000, v6
	s_nop 1
	v_addc_co_u32_e32 v29, vcc, 0, v7, vcc
	v_add_co_u32_e32 v30, vcc, 0x10000, v6
	s_nop 1
	v_addc_co_u32_e32 v31, vcc, 0, v7, vcc
	v_add_co_u32_e32 v6, vcc, 0x16000, v6
	s_nop 1
	v_addc_co_u32_e32 v7, vcc, 0, v7, vcc
	global_load_dwordx2 v[26:27], v[26:27], off
	s_nop 0
	global_load_dwordx2 v[28:29], v[28:29], off
	s_nop 0
	global_load_dwordx2 v[30:31], v[30:31], off
	s_nop 0
	global_load_dwordx2 v[32:33], v[6:7], off
	v_cndmask_b32_e64 v6, 0, 1, s[30:31]
	v_cmp_ne_u32_e64 s[8:9], 1, v6
	s_andn2_b64 vcc, exec, s[30:31]
	s_cbranch_vccnz .LBB0_2712
	s_lshl_b32 s0, s40, 11
	s_or_b32 s0, s41, s0
	v_add_u32_e32 v6, s0, v66
	v_ashrrev_i32_e32 v7, 31, v6
	v_lshlrev_b64 v[6:7], 7, v[6:7]
	v_lshl_add_u64 v[6:7], s[2:3], 0, v[6:7]
	s_lshl_b32 s14, s39, 2
	s_load_dwordx2 s[0:1], s[90:91], 0x98
	v_lshl_add_u64 v[6:7], v[6:7], 0, s[14:15]
	v_add_co_u32_e32 v60, vcc, 0x32b00000, v6
	s_nop 1
	v_addc_co_u32_e32 v61, vcc, 0, v7, vcc
	global_load_dword v59, v[60:61], off
	global_load_dword v84, v[60:61], off offset:64
	v_mov_b32_e32 v60, s14
	s_waitcnt lgkmcnt(0)
	global_load_dword v60, v60, s[0:1] offset:64
	s_load_dwordx2 s[70:71], s[90:91], 0x90
	v_mov_b32_e32 v86, s14
	s_waitcnt lgkmcnt(0)
	global_load_dword v85, v86, s[70:71] offset:64
	s_waitcnt vmcnt(0)
	v_add_f32_e32 v59, v59, v60
	v_cmp_nlt_f32_e32 vcc, s37, v59
	s_and_saveexec_b64 s[0:1], vcc
	s_cbranch_execz .LBB0_2711
	v_mul_f32_e32 v60, 0x3fb8aa3b, v59
	v_rndne_f32_e32 v61, v60
	v_sub_f32_e32 v63, v60, v61
	v_fma_f32 v60, v59, s38, -v60
	v_fmac_f32_e32 v60, 0x32a5705f, v59
	v_add_f32_e32 v60, v63, v60
	v_cvt_i32_f32_e32 v61, v61
	v_exp_f32_e32 v60, v60
	v_cmp_ngt_f32_e32 vcc, s34, v59
	s_mov_b32 s6, 0x3f2aaaab
	v_ldexp_f32 v60, v60, v61
	v_cndmask_b32_e32 v60, 0, v60, vcc
	v_cmp_nlt_f32_e32 vcc, s48, v59
	s_nop 1
	v_cndmask_b32_e32 v59, v138, v60, vcc
	v_add_f32_e32 v63, 1.0, v59
	v_add_f32_e32 v60, -1.0, v63
	v_sub_f32_e32 v61, v60, v63
	v_add_f32_e32 v61, 1.0, v61
	v_sub_f32_e32 v60, v59, v60
	v_add_f32_e32 v67, v60, v61
	v_frexp_mant_f32_e32 v68, v63
	v_cvt_f64_f32_e32 v[60:61], v63
	v_frexp_exp_i32_f64_e32 v60, v[60:61]
	v_cmp_gt_f32_e32 vcc, s6, v68
	s_mov_b32 s6, 0x3f317218
	s_nop 0
	v_subbrev_co_u32_e32 v76, vcc, 0, v60, vcc
	v_sub_u32_e32 v60, 0, v76
	v_ldexp_f32 v61, v63, v60
	v_add_f32_e32 v63, -1.0, v61
	v_add_f32_e32 v68, 1.0, v61
	v_ldexp_f32 v60, v67, v60
	v_add_f32_e32 v67, 1.0, v63
	v_add_f32_e32 v69, -1.0, v68
	v_sub_f32_e32 v67, v61, v67
	v_sub_f32_e32 v61, v61, v69
	v_add_f32_e32 v67, v60, v67
	v_add_f32_e32 v60, v60, v61
	v_add_f32_e32 v78, v68, v60
	v_rcp_f32_e32 v80, v78
	v_sub_f32_e32 v61, v68, v78
	v_add_f32_e32 v79, v60, v61
	v_add_f32_e32 v61, v63, v67
	v_sub_f32_e32 v60, v63, v61
	v_add_f32_e32 v63, v67, v60
	v_mul_f32_e32 v67, v61, v80
	v_mul_f32_e32 v68, v78, v67
	v_fma_f32 v70, v67, v78, -v68
	v_fmac_f32_e32 v70, v67, v79
	v_add_f32_e32 v60, v68, v70
	v_sub_f32_e32 v69, v61, v60
	v_pk_add_f32 v[72:73], v[60:61], v[68:69] neg_lo:[0,1] neg_hi:[0,1]
	v_mov_b32_e32 v71, v60
	v_pk_add_f32 v[60:61], v[72:73], v[70:71] neg_lo:[0,1] neg_hi:[0,1]
	s_nop 0
	v_add_f32_e32 v61, v63, v61
	v_add_f32_e32 v60, v60, v61
	v_add_f32_e32 v61, v69, v60
	v_mul_f32_e32 v63, v80, v61
	v_mul_f32_e32 v68, v78, v63
	v_fma_f32 v70, v63, v78, -v68
	v_fmac_f32_e32 v70, v63, v79
	v_sub_f32_e32 v69, v69, v61
	v_add_f32_e32 v78, v60, v69
	v_add_f32_e32 v60, v68, v70
	v_sub_f32_e32 v69, v61, v60
	v_pk_add_f32 v[72:73], v[60:61], v[68:69] neg_lo:[0,1] neg_hi:[0,1]
	v_mov_b32_e32 v71, v60
	v_pk_add_f32 v[60:61], v[72:73], v[70:71] neg_lo:[0,1] neg_hi:[0,1]
; __device__ __forceinline__ float lane_get(float v, int src_lane) { return __builtin_bit_cast(float, __builtin_amdgcn_ds_bpermute(src_lane << 2, __builtin_bit_cast(int, v))); }
; __device__ __forceinline__ void dprep_unit(const Ctx& c, int l, int b, int chunk, int h) {
;     ...
;         const float sp = xx > 20.f ? xx : log1pf(expf(xx));
;         float G = -expf(c.f(I_ALOG)[l * 16 + h]) * sp;
; #pragma unroll
;         for (int o = 1; o < 64; o <<= 1) { const float t = lane_get(G, lane - o); if (lane >= o) G += t; }
;         Gs[lane] = G; betas[lane] = 1.0f / (1.0f + expf(-AB[16 + h]));
	s_nop 0
	v_add_f32_e32 v61, v78, v61
	v_add_f32_e32 v60, v60, v61
	v_add_f32_e32 v61, v67, v63
	v_add_f32_e32 v60, v69, v60
	v_sub_f32_e32 v67, v61, v67
	v_mul_f32_e32 v60, v80, v60
	v_sub_f32_e32 v63, v63, v67
	v_add_f32_e32 v67, v63, v60
	v_add_f32_e32 v68, v61, v67
	v_mul_f32_e32 v70, v68, v68
	v_fmamk_f32 v60, v70, 0x3e9b6dac, v223
	v_fmaak_f32 v229, v70, v60, 0x3f2aaada
	v_cvt_f32_i32_e32 v60, v76
	v_sub_f32_e32 v61, v68, v61
	v_sub_f32_e32 v61, v67, v61
	v_ldexp_f32 v67, v61, 1
	v_mul_f32_e32 v61, v68, v70
	v_pk_mul_f32 v[70:71], v[60:61], v[228:229]
	v_ldexp_f32 v69, v68, 1
	v_fma_f32 v68, v60, s6, -v70
	v_fmac_f32_e32 v68, 0xb102e308, v60
	v_pk_add_f32 v[60:61], v[70:71], v[68:69]
	v_mov_b32_e32 v72, v70
	v_sub_f32_e32 v63, v61, v69
	v_sub_f32_e32 v63, v71, v63
	v_add_f32_e32 v73, v67, v63
	v_pk_add_f32 v[70:71], v[60:61], v[70:71] neg_lo:[0,1] neg_hi:[0,1]
	v_pk_add_f32 v[78:79], v[60:61], v[72:73]
	v_mov_b32_e32 v69, v60
	v_mov_b32_e32 v71, v79
	v_pk_add_f32 v[80:81], v[68:69], v[70:71] neg_lo:[0,1] neg_hi:[0,1]
	v_pk_add_f32 v[68:69], v[68:69], v[70:71]
	v_mov_b32_e32 v72, v73
	v_pk_add_f32 v[70:71], v[68:69], v[60:61] op_sel:[1,0] op_sel_hi:[0,1] neg_lo:[0,1] neg_hi:[0,1]
	v_pk_add_f32 v[82:83], v[78:79], v[70:71] op_sel_hi:[1,0] neg_lo:[0,1] neg_hi:[0,1]
	v_mov_b32_e32 v78, v79
	v_mov_b32_e32 v79, v69
	v_pk_mov_b32 v[70:71], v[60:61], v[70:71] op_sel:[1,0]
	v_mov_b32_e32 v73, v60
	v_pk_add_f32 v[70:71], v[78:79], v[70:71] neg_lo:[0,1] neg_hi:[0,1]
	v_mov_b32_e32 v82, v80
	v_pk_add_f32 v[60:61], v[72:73], v[70:71] neg_lo:[0,1] neg_hi:[0,1]
	v_mov_b32_e32 v81, v69
	v_pk_add_f32 v[70:71], v[82:83], v[60:61]
	s_mov_b32 s6, 0x7f800000
	v_pk_add_f32 v[72:73], v[70:71], v[70:71] op_sel:[0,1] op_sel_hi:[1,0]
	v_cmp_neq_f32_e32 vcc, s6, v59
	v_pk_add_f32 v[68:69], v[68:69], v[72:73] op_sel:[1,0] op_sel_hi:[0,1]
	v_mov_b32_e32 v71, v68
	v_pk_add_f32 v[78:79], v[70:71], v[80:81] neg_lo:[0,1] neg_hi:[0,1]
	v_mov_b32_e32 v61, v72
	v_sub_f32_e32 v63, v70, v78
	v_pk_add_f32 v[60:61], v[60:61], v[78:79] neg_lo:[0,1] neg_hi:[0,1]
	v_sub_f32_e32 v63, v80, v63
	v_add_f32_e32 v60, v60, v63
	v_add_f32_e32 v60, v60, v61
	v_add_f32_e32 v60, v68, v60
	s_mov_b32 s6, 0x33800000
	v_cndmask_b32_e32 v60, v138, v60, vcc
	v_cmp_lt_f32_e64 vcc, |v59|, s6
	s_nop 1
	v_cndmask_b32_e32 v59, v60, v59, vcc
.LBB0_2711:
	s_or_b64 exec, exec, s[0:1]
	s_mov_b64 s[0:1], 0x32b00000
	v_lshl_add_u64 v[6:7], v[6:7], 0, s[0:1]
	s_load_dwordx2 s[0:1], s[90:91], 0x90
	v_mov_b32_e32 v60, s14
	v_mov_b32_e32 v6, v84
	s_waitcnt vmcnt(0)
	v_mul_f32_e32 v7, 0xbfb8aa3b, v6
	s_waitcnt lgkmcnt(0)
	v_mov_b32_e32 v60, v85
	s_waitcnt vmcnt(0)
	v_mul_f32_e32 v61, 0x3fb8aa3b, v60
	v_fma_f32 v63, v60, s38, -v61
	v_rndne_f32_e32 v67, v61
	v_fmac_f32_e32 v63, 0x32a5705f, v60
	v_sub_f32_e32 v61, v61, v67
	v_add_f32_e32 v61, v61, v63
	v_exp_f32_e32 v61, v61
	v_cvt_i32_f32_e32 v63, v67
	v_cmp_ngt_f32_e32 vcc, s34, v60
	v_ldexp_f32 v61, v61, v63
	s_nop 0
	v_cndmask_b32_e32 v61, 0, v61, vcc
	v_cmp_nlt_f32_e32 vcc, s48, v60
	v_lshlrev_b32_e32 v63, 2, v66
	v_add_u32_e32 v67, -4, v63
	v_cndmask_b32_e32 v60, v138, v61, vcc
	v_mul_f32_e64 v61, v59, -v60
	ds_bpermute_b32 v67, v67, v61
	v_cmp_gt_i32_e32 vcc, 1, v66
	s_waitcnt lgkmcnt(0)
	v_fma_f32 v59, v59, -v60, v67
	v_cndmask_b32_e32 v59, v59, v61, vcc
	v_add_u32_e32 v60, -8, v63
	ds_bpermute_b32 v60, v60, v59
	v_cmp_gt_i32_e32 vcc, 2, v66
	v_rndne_f32_e32 v61, v7
	s_waitcnt lgkmcnt(0)
	v_add_f32_e32 v60, v59, v60
	v_cndmask_b32_e32 v59, v60, v59, vcc
	v_add_u32_e32 v60, -16, v63
	ds_bpermute_b32 v60, v60, v59
	v_cmp_gt_i32_e32 vcc, 4, v66
	s_waitcnt lgkmcnt(0)
	v_add_f32_e32 v60, v59, v60
	v_cndmask_b32_e32 v59, v60, v59, vcc
	v_subrev_u32_e32 v60, 32, v63
	ds_bpermute_b32 v60, v60, v59
	v_cmp_gt_i32_e32 vcc, 8, v66
	s_waitcnt lgkmcnt(0)
	v_add_f32_e32 v60, v59, v60
	v_cndmask_b32_e32 v59, v60, v59, vcc
	v_subrev_u32_e32 v60, 64, v63
	ds_bpermute_b32 v60, v60, v59
	v_cmp_gt_i32_e32 vcc, 16, v66
	s_waitcnt lgkmcnt(0)
	v_add_f32_e32 v60, v59, v60
	v_cndmask_b32_e32 v59, v60, v59, vcc
	v_add_u32_e32 v60, 0xffffff80, v63
	ds_bpermute_b32 v60, v60, v59
	v_cmp_gt_i32_e32 vcc, 32, v66
	s_waitcnt lgkmcnt(0)
	v_add_f32_e32 v60, v59, v60
	v_cndmask_b32_e32 v59, v60, v59, vcc
	v_add_u32_e32 v60, v156, v63
	v_sub_f32_e32 v63, v7, v61
	v_fma_f32 v7, v6, s63, -v7
	v_fmac_f32_e32 v7, 0xb2a5705f, v6
	v_add_f32_e32 v7, v63, v7
	v_exp_f32_e32 v7, v7
	v_cvt_i32_f32_e32 v61, v61
	v_cmp_nlt_f32_e32 vcc, s64, v6
	v_ldexp_f32 v7, v7, v61
	s_nop 0
	v_cndmask_b32_e32 v7, 0, v7, vcc
	v_cmp_ngt_f32_e32 vcc, s65, v6
	s_nop 1
	v_cndmask_b32_e32 v6, v138, v7, vcc
	v_add_f32_e32 v6, 1.0, v6
	v_div_scale_f32 v7, s[0:1], v6, v6, 1.0
	v_rcp_f32_e32 v61, v7
	s_nop 0
	v_fma_f32 v63, -v7, v61, 1.0
	v_fmac_f32_e32 v61, v63, v61
	v_div_scale_f32 v63, vcc, 1.0, v6, 1.0
	v_mul_f32_e32 v67, v63, v61
	v_fma_f32 v68, -v7, v67, v63
	v_fmac_f32_e32 v67, v68, v61
	v_fma_f32 v7, -v7, v67, v63
	v_div_fmas_f32 v7, v7, v61, v67
	v_div_fixup_f32 v6, v7, v6, 1.0
	ds_write2st64_b32 v60, v59, v6 offset1:1

;     template <class T> __device__ __forceinline__ T* w(size_t off) const { return (T*)(pp->ws + off); }
; __device__ __forceinline__ void dprep_unit(const Ctx& c, int l, int b, int chunk, int h) {
;     ...
;     float wq[4][2], wk[4][2], wv[4][2];
;     const float* cw = c.f(I_CONVW) + (size_t)l * 4 * 6144 + h * 128 + 2 * lane;
; #pragma unroll
;     for (int j = 0; j < 4; ++j) { wq[j][0] = cw[j * 6144]; wq[j][1] = cw[j * 6144 + 1]; wk[j][0] = cw[j * 6144 + 2048]; wk[j][1] = cw[j * 6144 + 2049]; wv[j][0] = cw[j * 6144 + 4096]; wv[j][1] = cw[j * 6144 + 4097]; }
;     if (wave == 0) {
;         const float* AB = c.w<float>(WS_AB) + (size_t)(row0 + lane) * 32;
;         const float xx = AB[h] + c.f(I_DTB)[l * 16 + h];
;         const float sp = xx > 20.f ? xx : log1pf(expf(xx));
;         float G = -expf(c.f(I_ALOG)[l * 16 + h]) * sp;
.LBB0_2769:
	s_lshl_b32 s0, s30, 7
	s_lshl_b32 s0, s0, 2
	s_add_u32 s0, s46, s0
	s_addc_u32 s1, s47, 0
	v_lshl_add_u64 v[38:39], v[4:5], 2, s[0:1]
	s_movk_i32 s0, 0x6000
	v_add_co_u32_e32 v0, vcc, s0, v38
	s_mov_b32 s0, 0xc000
	s_nop 0
	v_addc_co_u32_e32 v1, vcc, 0, v39, vcc
	v_add_co_u32_e32 v2, vcc, s0, v38
	s_movk_i32 s0, 0x2000
	s_nop 0
	v_addc_co_u32_e32 v3, vcc, 0, v39, vcc
	v_add_co_u32_e32 v4, vcc, s35, v38
	s_mov_b32 s42, 0xc2ce8ed0
	s_nop 0
	v_addc_co_u32_e32 v5, vcc, 0, v39, vcc
	global_load_dwordx2 v[46:47], v[38:39], off
	global_load_dwordx2 v[48:49], v[0:1], off
	global_load_dwordx2 v[50:51], v[2:3], off
	global_load_dwordx2 v[52:53], v[4:5], off
	v_add_co_u32_e32 v0, vcc, s0, v38
	s_mov_b32 s0, 0x8000
	s_nop 0
	v_addc_co_u32_e32 v1, vcc, 0, v39, vcc
	v_add_co_u32_e32 v2, vcc, s0, v38
	s_mov_b32 s0, 0xe000
	s_nop 0
	v_addc_co_u32_e32 v3, vcc, 0, v39, vcc
	v_add_co_u32_e32 v4, vcc, s0, v38
	s_mov_b32 s0, 0x14000
	s_nop 0
	v_addc_co_u32_e32 v5, vcc, 0, v39, vcc
	v_add_co_u32_e32 v36, vcc, s0, v38
	s_movk_i32 s0, 0x4000
	s_nop 0
	v_addc_co_u32_e32 v37, vcc, 0, v39, vcc
	v_add_co_u32_e32 v40, vcc, s0, v38
	global_load_dwordx2 v[0:1], v[0:1], off
	s_nop 0
	global_load_dwordx2 v[2:3], v[2:3], off
	s_nop 0
	global_load_dwordx2 v[4:5], v[4:5], off
	s_nop 0
	global_load_dwordx2 v[36:37], v[36:37], off
	v_addc_co_u32_e32 v41, vcc, 0, v39, vcc
	v_add_co_u32_e32 v42, vcc, 0xa000, v38
	s_nop 1
	v_addc_co_u32_e32 v43, vcc, 0, v39, vcc
	v_add_co_u32_e32 v44, vcc, 0x10000, v38
	s_nop 1
	v_addc_co_u32_e32 v45, vcc, 0, v39, vcc
	v_add_co_u32_e32 v54, vcc, 0x16000, v38
	s_nop 1
	v_addc_co_u32_e32 v55, vcc, 0, v39, vcc
	global_load_dwordx2 v[38:39], v[40:41], off
	s_nop 0
	global_load_dwordx2 v[40:41], v[42:43], off
	s_nop 0
	global_load_dwordx2 v[42:43], v[44:45], off
	s_nop 0
	global_load_dwordx2 v[44:45], v[54:55], off
	s_and_b64 vcc, exec, s[8:9]
	s_cbranch_vccnz .LBB0_2773
	s_lshl_b32 s0, s40, 11
	s_or_b32 s0, s41, s0
	v_add_u32_e32 v54, s0, v66
	v_ashrrev_i32_e32 v55, 31, v54
	s_load_dwordx2 s[0:1], s[90:91], 0x98
	v_lshlrev_b64 v[54:55], 7, v[54:55]
	v_lshl_add_u64 v[54:55], s[2:3], 0, v[54:55]
	s_lshl_b32 s14, s39, 2
	v_lshl_add_u64 v[54:55], v[54:55], 0, s[14:15]
	s_mov_b64 s[4:5], 0x32b00000
	v_lshl_add_u64 v[54:55], v[54:55], 0, s[4:5]
	v_mov_b32_e32 v63, s14
	global_load_dword v61, v[54:55], off offset:32
	global_load_dword v112, v[54:55], off offset:96
	s_waitcnt lgkmcnt(0)
	global_load_dword v63, v63, s[0:1] offset:96
	s_load_dwordx2 s[70:71], s[90:91], 0x90
	v_mov_b32_e32 v114, s14
	s_waitcnt lgkmcnt(0)
	global_load_dword v113, v114, s[70:71] offset:96
	s_waitcnt vmcnt(0)
	v_add_f32_e32 v61, v61, v63
	v_cmp_nlt_f32_e32 vcc, s59, v61
	s_and_saveexec_b64 s[0:1], vcc
	s_cbranch_execz .LBB0_2772
	v_mul_f32_e32 v63, 0x3fb8aa3b, v61
	v_rndne_f32_e32 v94, v63
	v_sub_f32_e32 v95, v63, v94
	v_fma_f32 v63, v61, s62, -v63
	v_fmac_f32_e32 v63, 0x32a5705f, v61
	v_add_f32_e32 v63, v95, v63
	v_cvt_i32_f32_e32 v94, v94
	v_exp_f32_e32 v63, v63
	v_cmp_ngt_f32_e32 vcc, s42, v61
	s_mov_b32 s4, 0x3f2aaaab
	v_ldexp_f32 v63, v63, v94
	v_cndmask_b32_e32 v63, 0, v63, vcc
	v_cmp_nlt_f32_e32 vcc, s43, v61
	s_nop 1
	v_cndmask_b32_e32 v61, v138, v63, vcc
	v_add_f32_e32 v63, 1.0, v61
	v_add_f32_e32 v94, -1.0, v63
	v_sub_f32_e32 v95, v94, v63
	v_add_f32_e32 v95, 1.0, v95
	v_sub_f32_e32 v94, v61, v94
	v_add_f32_e32 v99, v94, v95
	v_frexp_mant_f32_e32 v100, v63
	v_cvt_f64_f32_e32 v[94:95], v63
	v_frexp_exp_i32_f64_e32 v94, v[94:95]
	v_cmp_gt_f32_e32 vcc, s4, v100
	s_mov_b32 s4, 0x3f317218
	s_nop 0
	v_subbrev_co_u32_e32 v106, vcc, 0, v94, vcc
	v_sub_u32_e32 v94, 0, v106
	v_ldexp_f32 v63, v63, v94
	v_ldexp_f32 v94, v99, v94
	v_add_f32_e32 v99, -1.0, v63
	v_add_f32_e32 v95, 1.0, v99
	v_sub_f32_e32 v95, v63, v95
	v_add_f32_e32 v100, v94, v95
	v_add_f32_e32 v95, 1.0, v63
	v_add_f32_e32 v101, -1.0, v95
	v_sub_f32_e32 v63, v63, v101
	v_add_f32_e32 v63, v94, v63
	v_add_f32_e32 v107, v95, v63
	v_rcp_f32_e32 v108, v107
	v_sub_f32_e32 v94, v95, v107
	v_add_f32_e32 v95, v99, v100
	v_add_f32_e32 v63, v63, v94
	v_sub_f32_e32 v94, v99, v95
	v_mul_f32_e32 v109, v95, v108
	v_add_f32_e32 v99, v100, v94
	v_mul_f32_e32 v100, v107, v109
	v_fma_f32 v102, v109, v107, -v100
	v_fmac_f32_e32 v102, v109, v63
	v_add_f32_e32 v94, v100, v102
	v_sub_f32_e32 v101, v95, v94
	v_pk_add_f32 v[104:105], v[94:95], v[100:101] neg_lo:[0,1] neg_hi:[0,1]
	v_mov_b32_e32 v103, v94
	v_pk_add_f32 v[94:95], v[104:105], v[102:103] neg_lo:[0,1] neg_hi:[0,1]
	s_nop 0
	v_add_f32_e32 v95, v99, v95
	v_add_f32_e32 v94, v94, v95
	v_add_f32_e32 v95, v101, v94
	v_mul_f32_e32 v99, v108, v95
	v_mul_f32_e32 v100, v107, v99
	v_fma_f32 v102, v99, v107, -v100
	v_fmac_f32_e32 v102, v99, v63
	v_sub_f32_e32 v63, v101, v95
	v_add_f32_e32 v63, v94, v63
	v_add_f32_e32 v94, v100, v102
	v_sub_f32_e32 v101, v95, v94
	v_pk_add_f32 v[104:105], v[94:95], v[100:101] neg_lo:[0,1] neg_hi:[0,1]
	v_mov_b32_e32 v103, v94
	v_pk_add_f32 v[94:95], v[104:105], v[102:103] neg_lo:[0,1] neg_hi:[0,1]
	s_nop 0
	v_add_f32_e32 v63, v63, v95
	v_add_f32_e32 v63, v94, v63
; __device__ __forceinline__ float lane_get(float v, int src_lane) { return __builtin_bit_cast(float, __builtin_amdgcn_ds_bpermute(src_lane << 2, __builtin_bit_cast(int, v))); }
; __device__ __forceinline__ void dprep_unit(const Ctx& c, int l, int b, int chunk, int h) {
;     ...
;         const float sp = xx > 20.f ? xx : log1pf(expf(xx));
;         float G = -expf(c.f(I_ALOG)[l * 16 + h]) * sp;
; #pragma unroll
;         for (int o = 1; o < 64; o <<= 1) { const float t = lane_get(G, lane - o); if (lane >= o) G += t; }
;         Gs[lane] = G; betas[lane] = 1.0f / (1.0f + expf(-AB[16 + h]));
	v_add_f32_e32 v95, v109, v99
	v_add_f32_e32 v63, v101, v63
	v_sub_f32_e32 v94, v95, v109
	v_mul_f32_e32 v63, v108, v63
	v_sub_f32_e32 v94, v99, v94
	v_add_f32_e32 v99, v94, v63
	v_add_f32_e32 v100, v95, v99
	v_cvt_f32_i32_e32 v94, v106
	v_mul_f32_e32 v102, v100, v100
	v_sub_f32_e32 v95, v100, v95
	v_fmamk_f32 v63, v102, 0x3e9b6dac, v223
	v_sub_f32_e32 v95, v99, v95
	v_fmaak_f32 v229, v102, v63, 0x3f2aaada
	v_ldexp_f32 v99, v95, 1
	v_mul_f32_e32 v95, v100, v102
	v_pk_mul_f32 v[102:103], v[94:95], v[228:229]
	v_ldexp_f32 v101, v100, 1
	v_fma_f32 v100, v94, s4, -v102
	v_fmac_f32_e32 v100, 0xb102e308, v94
	v_pk_add_f32 v[94:95], v[102:103], v[100:101]
	v_mov_b32_e32 v104, v102
	v_sub_f32_e32 v63, v95, v101
	v_sub_f32_e32 v63, v103, v63
	v_add_f32_e32 v105, v99, v63
	v_pk_add_f32 v[102:103], v[94:95], v[102:103] neg_lo:[0,1] neg_hi:[0,1]
	v_pk_add_f32 v[106:107], v[94:95], v[104:105]
	v_mov_b32_e32 v101, v94
	v_mov_b32_e32 v103, v107
	v_pk_add_f32 v[108:109], v[100:101], v[102:103] neg_lo:[0,1] neg_hi:[0,1]
	v_pk_add_f32 v[100:101], v[100:101], v[102:103]
	v_mov_b32_e32 v104, v105
	v_pk_add_f32 v[102:103], v[100:101], v[94:95] op_sel:[1,0] op_sel_hi:[0,1] neg_lo:[0,1] neg_hi:[0,1]
	v_pk_add_f32 v[110:111], v[106:107], v[102:103] op_sel_hi:[1,0] neg_lo:[0,1] neg_hi:[0,1]
	v_mov_b32_e32 v106, v107
	v_mov_b32_e32 v107, v101
	v_pk_mov_b32 v[102:103], v[94:95], v[102:103] op_sel:[1,0]
	v_mov_b32_e32 v105, v94
	v_pk_add_f32 v[102:103], v[106:107], v[102:103] neg_lo:[0,1] neg_hi:[0,1]
	v_mov_b32_e32 v110, v108
	v_pk_add_f32 v[94:95], v[104:105], v[102:103] neg_lo:[0,1] neg_hi:[0,1]
	v_mov_b32_e32 v109, v101
	v_pk_add_f32 v[102:103], v[110:111], v[94:95]
	s_mov_b32 s4, 0x7f800000
	v_pk_add_f32 v[104:105], v[102:103], v[102:103] op_sel:[0,1] op_sel_hi:[1,0]
	v_cmp_neq_f32_e32 vcc, s4, v61
	v_pk_add_f32 v[100:101], v[100:101], v[104:105] op_sel:[1,0] op_sel_hi:[0,1]
	v_mov_b32_e32 v103, v100
	v_pk_add_f32 v[106:107], v[102:103], v[108:109] neg_lo:[0,1] neg_hi:[0,1]
	v_mov_b32_e32 v95, v104
	v_sub_f32_e32 v63, v102, v106
	v_pk_add_f32 v[94:95], v[94:95], v[106:107] neg_lo:[0,1] neg_hi:[0,1]
	v_sub_f32_e32 v63, v108, v63
	v_add_f32_e32 v63, v94, v63
	v_add_f32_e32 v63, v63, v95
	v_add_f32_e32 v63, v100, v63
	s_mov_b32 s4, 0x33800000
	v_cndmask_b32_e32 v63, v138, v63, vcc
	v_cmp_lt_f32_e64 vcc, |v61|, s4
	s_nop 1
	v_cndmask_b32_e32 v61, v63, v61, vcc
.LBB0_2772:
	s_or_b64 exec, exec, s[0:1]
	s_load_dwordx2 s[0:1], s[90:91], 0x90
	v_mov_b32_e32 v63, s14
	v_mov_b32_e32 v54, v112
	s_waitcnt vmcnt(0)
	v_mul_f32_e32 v55, 0xbfb8aa3b, v54
	s_waitcnt lgkmcnt(0)
	v_mov_b32_e32 v63, v113
	s_waitcnt vmcnt(0)
	v_mul_f32_e32 v94, 0x3fb8aa3b, v63
	v_fma_f32 v95, v63, s62, -v94
	v_rndne_f32_e32 v99, v94
	v_fmac_f32_e32 v95, 0x32a5705f, v63
	v_sub_f32_e32 v94, v94, v99
	v_add_f32_e32 v94, v94, v95
	v_exp_f32_e32 v94, v94
	v_cvt_i32_f32_e32 v95, v99
	v_cmp_ngt_f32_e32 vcc, s42, v63
	v_ldexp_f32 v94, v94, v95
	s_nop 0
	v_cndmask_b32_e32 v94, 0, v94, vcc
	v_cmp_nlt_f32_e32 vcc, s43, v63
	v_add_u32_e32 v95, -4, v60
	s_nop 0
	v_cndmask_b32_e32 v63, v138, v94, vcc
	v_mul_f32_e64 v94, v61, -v63
	ds_bpermute_b32 v95, v95, v94
	v_cmp_gt_i32_e32 vcc, 1, v66
	s_waitcnt lgkmcnt(0)
	v_fma_f32 v61, v61, -v63, v95
	v_cndmask_b32_e32 v61, v61, v94, vcc
	v_add_u32_e32 v63, -8, v60
	ds_bpermute_b32 v63, v63, v61
	v_cmp_gt_i32_e32 vcc, 2, v66
	s_waitcnt lgkmcnt(0)
	v_add_f32_e32 v63, v61, v63
	v_cndmask_b32_e32 v61, v63, v61, vcc
	v_add_u32_e32 v63, -16, v60
	ds_bpermute_b32 v63, v63, v61
	v_cmp_gt_i32_e32 vcc, 4, v66
	s_waitcnt lgkmcnt(0)
	v_add_f32_e32 v63, v61, v63
	v_cndmask_b32_e32 v61, v63, v61, vcc
	v_subrev_u32_e32 v63, 32, v60
	ds_bpermute_b32 v63, v63, v61
	v_cmp_gt_i32_e32 vcc, 8, v66
	s_waitcnt lgkmcnt(0)
	v_add_f32_e32 v63, v61, v63
	v_cndmask_b32_e32 v61, v63, v61, vcc
	v_subrev_u32_e32 v63, 64, v60
	ds_bpermute_b32 v63, v63, v61
	v_cmp_gt_i32_e32 vcc, 16, v66
	v_add_u32_e32 v60, 0xffffff80, v60
	s_waitcnt lgkmcnt(0)
	v_add_f32_e32 v63, v61, v63
	v_cndmask_b32_e32 v61, v63, v61, vcc
	v_rndne_f32_e32 v63, v55
	v_sub_f32_e32 v94, v55, v63
	v_fma_f32 v55, v54, s63, -v55
	ds_bpermute_b32 v60, v60, v61
	v_fmac_f32_e32 v55, 0xb2a5705f, v54
	v_add_f32_e32 v55, v94, v55
	v_exp_f32_e32 v55, v55
	v_cvt_i32_f32_e32 v63, v63
	v_cmp_gt_i32_e32 vcc, 32, v66
	s_waitcnt lgkmcnt(0)
	v_add_f32_e32 v60, v61, v60
	v_ldexp_f32 v55, v55, v63
	v_cndmask_b32_e32 v60, v60, v61, vcc
	v_cmp_nlt_f32_e32 vcc, s64, v54
	v_lshl_add_u32 v61, v66, 2, v169
	s_nop 0
	v_cndmask_b32_e32 v55, 0, v55, vcc
	v_cmp_ngt_f32_e32 vcc, s65, v54
	s_nop 1
	v_cndmask_b32_e32 v54, v138, v55, vcc
	v_add_f32_e32 v54, 1.0, v54
	v_div_scale_f32 v55, s[0:1], v54, v54, 1.0
	v_rcp_f32_e32 v63, v55
	s_nop 0
	v_fma_f32 v94, -v55, v63, 1.0
	v_fmac_f32_e32 v63, v94, v63
	v_div_scale_f32 v94, vcc, 1.0, v54, 1.0
	v_mul_f32_e32 v95, v94, v63
	v_fma_f32 v99, -v55, v95, v94
	v_fmac_f32_e32 v95, v99, v63
	v_fma_f32 v55, -v55, v95, v94
	v_div_fmas_f32 v55, v55, v63, v95
	v_div_fixup_f32 v54, v55, v54, 1.0
	ds_write2st64_b32 v61, v60, v54 offset1:1
